# G1 unit order remapped: 4 weight column tiles stay fixed across 16 consecutive rounds per XCD (B panel 2 MiB L2-resident), row tiles advance each round; bijective wgid->(pm,pn) remap in both decode si
# baseline (speedup 1.0000x reference)
; __host__ __device__ __forceinline__ int xcd_remap(int L, int nwg) { const int q = nwg / NXCD, r = nwg % NXCD, xcd = L % NXCD, off = L / NXCD; return (xcd < r ? xcd * (q + 1) : r * (q + 1) + (xcd - r) * q) + off; }
; __host__ __device__ __forceinline__ bool order_mn(int L, int nM, int nN, Unit& u) {
;     const int nwg = nM * nN; if (L >= nwg) return false;
;     const int wgid = xcd_remap(L, nwg);
;     const int nig = WGM * nN, gid = wgid / nig, fm = gid * WGM, gsz = (nM - fm) < WGM ? (nM - fm) : WGM;
;     u.pm = fm + ((wgid % nig) % gsz); u.pn = (wgid % nig) / gsz; u.g = 0; u.ks = 0; return true;
; template <class P>
; __device__ __forceinline__ void gemm_phase(LAS unsigned char* lds, const P& p, const int G, const int c) {
;     ...
;     { int R, C; stage_rc(tid * 16, R, C); const int Rb = P::PERM ? ((R & ~31) + perm32(R & 31)) : R;
;       voffA0 = (unsigned)(p.a_off(0, R, C) - p.a_off(0, 0, 0) + p.a_bias(0)); voffB0 = (unsigned)(p.b_off(0, Rb, C) - p.b_off(0, 0, 0) + p.b_bias(0));
;       voffA1 = (unsigned)(p.a_off(S1, R, C) - p.a_off(S1, 0, 0) + p.a_bias(S1)); voffB1 = (unsigned)(p.b_off(S1, Rb, C) - p.b_off(S1, 0, 0) + p.b_bias(S1)); }
;     const long r64A0 = p.a_off(0, 64, 0) - p.a_off(0, 0, 0), r64A1 = p.a_off(S1, 64, 0) - p.a_off(S1, 0, 0), r64B0 = p.b_off(0, 64, 0) - p.b_off(0, 0, 0), r64B1 = p.b_off(S1, 64, 0) - p.b_off(S1, 0, 0);
;     const long hA0 = p.a_off(0, 128, 0) - p.a_off(0, 0, 0), hA1 = p.a_off(S1, 128, 0) - p.a_off(S1, 0, 0), hB0 = p.b_off(0, 128, 0) - p.b_off(0, 0, 0), hB1 = p.b_off(S1, 128, 0) - p.b_off(S1, 0, 0);
;     const long ksA0 = p.a_off(0, 0, 64) - p.a_off(0, 0, 0), ksA1 = p.a_off(S1, 0, 64) - p.a_off(S1, 0, 0), ksB0 = p.b_off(0, 0, 64) - p.b_off(0, 0, 0), ksB1 = p.b_off(S1, 0, 64) - p.b_off(S1, 0, 0);
;     const unsigned ldsw = (unsigned)wid * 1024u;
;     const int aoff = lds_byte(wr * 64 + fr, fq * 8), boff = lds_byte(wc * 32 + fr, fq * 8);
;     ...
;     Unit cur, nxt; int ui = 0;
;     if (!p.unit(c, cur)) return;
;     Acc acc;
; #pragma unroll
;     for (int a = 0; a < 2; ++a)
; #pragma unroll
;         for (int b = 0; b < 2; ++b)
; #pragma unroll
;             for (int m = 0; m < 4; ++m)
; #pragma unroll
;                 for (int n = 0; n < 2; ++n) acc[a][b][m][n] = (f32x4){0.f, 0.f, 0.f, 0.f};
;     bf16x8 At[4][2], B0[2][2], B1[2][2];
.LBB0_144:
	v_mov_b32_e32 v10, v0
	s_cmpk_lt_i32 s92, 0x1040
	s_cselect_b64 s[4:5], -1, 0
	s_cmpk_gt_i32 s92, 0x103f
	v_readfirstlane_b32 s18, v10
	s_cbranch_scc1 .LBB0_146
	s_ashr_i32 s2, s92, 31
	s_lshr_b32 s2, s2, 29
	s_add_i32 s2, s92, s2
	s_and_b32 s3, s2, -8
	s_sub_i32 s3, s92, s3
	s_cmp_lt_i32 s3, 0
	s_movk_i32 s6, 0x209
	s_cselect_b32 s6, s6, 0x208
	s_mul_i32 s3, s6, s3
	s_ashr_i32 s2, s2, 3
	s_add_i32 s2, s3, s2
	s_cmpk_lt_u32 s2, 0x1000
	s_cbranch_scc0 .Lg1o_ctx_a
	s_bfe_u32 s3, s2, 0x40005
	s_lshl_b32 s3, s3, 3
	s_and_b32 s6, s2, 7
	s_add_i32 s80, s3, s6
	s_lshr_b32 s3, s2, 9
	s_lshl_b32 s3, s3, 2
	s_bfe_u32 s6, s2, 0x20003
	s_add_i32 s78, s3, s6
	s_branch .Lg1o_done_a
.Lg1o_ctx_a:
	s_sub_i32 s3, s2, 0x1000
	s_and_b32 s6, s3, 1
	s_add_i32 s80, s6, 0x80
	s_lshr_b32 s78, s3, 1
.Lg1o_done_a:
.LBB0_146:
	s_andn2_b64 vcc, exec, s[4:5]
	s_cbranch_vccnz .LBB0_183
	v_bfe_i32 v1, v10, 27, 1
	v_lshlrev_b32_e32 v2, 4, v10
	v_lshrrev_b32_e32 v1, 22, v1
	s_ashr_i32 s12, s18, 6
	v_add_u32_e32 v1, v2, v1
	s_ashr_i32 s19, s18, 8
	s_lshl_b32 s2, s12, 10
	v_and_b32_e32 v1, 0xfffffc00, v1
	s_add_u32 s3, s56, 0x6200000
	v_sub_u32_e32 v1, v2, v1
	s_addc_u32 s24, s57, 0
	v_lshrrev_b32_e32 v2, 4, v1
	s_add_u32 s25, s56, 0x1e400000
	v_bitop3_b32 v1, v2, v1, 32 bitop3:0x6c
	s_addc_u32 s26, s57, 0
	v_ashrrev_i32_e32 v2, 31, v1
	v_ashrrev_i32_e32 v3, 31, v10
	s_cmp_lt_i32 s78, 16
	v_lshrrev_b32_e32 v2, 26, v2
	v_lshrrev_b32_e32 v3, 26, v3
	s_cselect_b64 s[4:5], -1, 0
	s_cmpk_gt_i32 s80, 0x7f
	v_add_u32_e32 v2, v1, v2
	v_add_u32_e32 v3, v10, v3
	s_cselect_b64 s[6:7], -1, 0
	v_and_b32_e32 v4, 0xc0, v2
	v_ashrrev_i32_e32 v3, 6, v3
	s_or_b64 s[4:5], s[4:5], s[6:7]
	v_readlane_b32 s36, v253, 7
	v_sub_u32_e32 v1, v1, v4
	v_lshlrev_b32_e32 v4, 5, v3
	v_mov_b32_e32 v5, 1
	s_and_b64 s[4:5], s[4:5], exec
	v_readlane_b32 s50, v253, 21
	v_readlane_b32 s51, v253, 22
	v_ashrrev_i16_sdwa v1, v5, sext(v1) dst_sel:DWORD dst_unused:UNUSED_PAD src0_sel:DWORD src1_sel:BYTE_0
	v_and_b32_e32 v4, 32, v4
	s_cselect_b32 s6, s24, s51
	s_cselect_b32 s7, s3, s50
	s_ashr_i32 s81, s80, 31
	v_add_u32_sdwa v1, v4, sext(v1) dst_sel:DWORD dst_unused:UNUSED_PAD src0_sel:DWORD src1_sel:WORD_0
	v_lshlrev_b32_e32 v3, 3, v3
	s_lshl_b64 s[4:5], s[80:81], 15
	v_ashrrev_i32_e32 v2, 6, v2
	v_ashrrev_i32_e32 v6, 6, v1
	v_and_b32_e32 v3, 0x1fffff0, v3
	s_add_u32 s82, s7, s4
	v_add_u32_e32 v2, v2, v3
	v_mul_i32_i24_e32 v3, 0x410000, v6
	v_lshlrev_b32_e32 v1, 1, v1
	s_addc_u32 s83, s6, s5
	s_ashr_i32 s79, s78, 31
	v_lshl_add_u32 v2, v2, 7, v3
	v_and_b32_e32 v4, 0x7e, v1
	v_mul_i32_i24_e32 v1, 0xffcf0000, v6
	s_lshl_b64 s[4:5], s[78:79], 15
	v_mov_b32_e32 v5, 0
	v_add_u32_e32 v1, v2, v1
	s_add_u32 s28, s25, s4
	s_addc_u32 s29, s26, s5
	v_or_b32_e32 v142, v1, v4
	v_mov_b32_e32 v143, v5
	s_add_i32 s27, s2, 0
	v_lshl_add_u64 v[6:7], s[28:29], 0, v[142:143]
	s_add_i32 m0, s27, 0x10000
	s_mov_b64 s[4:5], 0x2000
	global_load_lds_dwordx4 v142, s[28:29]
	v_lshl_add_u64 v[8:9], v[6:7], 0, s[4:5]
	s_add_i32 m0, s27, 0x12000
	s_mov_b64 s[6:7], 0x4000
	global_load_lds_dwordx4 v[8:9], off
	v_lshl_add_u64 v[8:9], v[6:7], 0, s[6:7]
	s_add_i32 m0, s27, 0x14000
	s_mov_b64 s[8:9], 0x6000
	global_load_lds_dwordx4 v[8:9], off
	v_lshl_add_u64 v[8:9], v[6:7], 0, s[8:9]
	s_add_i32 m0, s27, 0x16000
	v_or_b32_e32 v144, v2, v4
	v_mov_b32_e32 v145, v5
	global_load_lds_dwordx4 v[8:9], off
	v_lshl_add_u64 v[8:9], s[82:83], 0, v[144:145]
	s_mov_b32 m0, s27
	s_add_i32 s33, s27, 0x2000
	global_load_lds_dwordx4 v[8:9], off
	v_lshl_add_u64 v[12:13], v[8:9], 0, s[4:5]
	s_mov_b32 m0, s33
	s_add_i32 s34, s27, 0x4000
	global_load_lds_dwordx4 v[12:13], off
	v_lshl_add_u64 v[12:13], v[8:9], 0, s[6:7]
	s_mov_b32 m0, s34
	s_add_i32 s35, s27, 0x6000
	global_load_lds_dwordx4 v[12:13], off
	v_lshl_add_u64 v[12:13], v[8:9], 0, s[8:9]
	s_mov_b32 m0, s35
	v_readlane_b32 s44, v253, 15
	global_load_lds_dwordx4 v[12:13], off
	s_cmp_eq_u32 s19, 1
	s_mov_b32 s44, 0
	s_cselect_b64 s[10:11], -1, 0
	s_cmp_lg_u32 s19, 1
	v_mov_b32_e32 v3, v5
	v_readlane_b32 s37, v253, 8
	v_readlane_b32 s38, v253, 9
	v_readlane_b32 s39, v253, 10
	v_readlane_b32 s40, v253, 11
	v_readlane_b32 s41, v253, 12
	v_readlane_b32 s42, v253, 13
	v_readlane_b32 s43, v253, 14
	v_readlane_b32 s45, v253, 16
	v_readlane_b32 s46, v253, 17
	v_readlane_b32 s47, v253, 18
	v_readlane_b32 s48, v253, 19
	v_readlane_b32 s49, v253, 20
	s_cbranch_scc1 .LBB0_149
	s_barrier

; #define G8_STA(bufoff, ptr, sg, h) G8_STAGE1(bufoff, (ptr) + (h) * ((sg) ? hA1 : hA0), ((sg) ? voffA1 : voffA0), ((sg) ? r64A1 : r64A0))
; #define G8_WAIT_V(n) asm volatile("s_waitcnt vmcnt(" #n ")" ::: "memory")
; #define G8_BAR __builtin_amdgcn_s_barrier()
; __host__ __device__ __forceinline__ int xcd_remap(int L, int nwg) { const int q = nwg / NXCD, r = nwg % NXCD, xcd = L % NXCD, off = L / NXCD; return (xcd < r ? xcd * (q + 1) : r * (q + 1) + (xcd - r) * q) + off; }
; __host__ __device__ __forceinline__ bool order_mn(int L, int nM, int nN, Unit& u) {
;     const int nwg = nM * nN; if (L >= nwg) return false;
;     const int wgid = xcd_remap(L, nwg);
;     const int nig = WGM * nN, gid = wgid / nig, fm = gid * WGM, gsz = (nM - fm) < WGM ? (nM - fm) : WGM;
;     u.pm = fm + ((wgid % nig) % gsz); u.pn = (wgid % nig) / gsz; u.g = 0; u.ks = 0; return true;
; template <class P>
; __device__ __forceinline__ void gemm_phase(LAS unsigned char* lds, const P& p, const int G, const int c) {
;     ...
;         const bool has_next = p.unit((ui + 1) * G + c, nxt);
;         const int nt = p.nt(cur);
;         const char* nA0 = has_next ? p.a_base(nxt, 0) - p.a_bias(0) : cA0; const char* nA1 = has_next ? p.a_base(nxt, S1) - p.a_bias(S1) : cA1;
;         const char* nB0 = has_next ? p.b_base(nxt, 0) - p.b_bias(0) : cB0; const char* nB1 = has_next ? p.b_base(nxt, S1) - p.b_bias(S1) : cB1;
;         for (int t = 0; t < nt; t += 2) {
;             const bool last = (t == nt - 2);
;             const bool sg1 = (NS > 1) && (t + 1 >= nt0);
;             const bool sg2 = (NS > 1) && !last && (t + 2 >= nt0);
;             const char* a1 = sg1 ? cA1 + (long)(t + 1 - nt0) * ksA1 : cA0 + (long)(t + 1) * ksA0;
;             const char* a2 = last ? nA0 : (sg2 ? cA1 + (long)(t + 2 - nt0) * ksA1 : cA0 + (long)(t + 2) * ksA0);
;             const char* b2 = last ? nB0 : (sg2 ? cB1 + (long)(t + 2 - nt0) * ksB1 : cB0 + (long)(t + 2) * ksB0);
;             const char* a3 = a2 + (sg2 ? ksA1 : ksA0); const char* b3 = b2 + (sg2 ? ksB1 : ksB0);
;             G8_LDB(B0, 0, 0); G8_LDB(B1, 0, 1); G8_SCHED; G8_LDA(At, 0, 0); G8_STA(G8_SA(1, 1), a1, sg1, 1);
;             G8_WAIT_V(8); G8_WAIT_L(0); G8_BAR; G8_MMA(0, 0, At, B0); G8_MMA(0, 1, At, B1); G8_BAR; G8_SCHED;
;             G8_LDA(At, 0, 1); G8_STB(G8_SB(0, 0), b2, sg2, 0); G8_STB(G8_SB(0, 1), b2, sg2, 1); G8_STA(G8_SA(0, 0), a2, sg2, 0);
.LBB0_152:
	s_add_i32 s44, s44, 1
	s_mul_i32 s18, s44, s84
	s_add_i32 s18, s18, s92
	s_cmpk_lt_i32 s18, 0x1040
	s_cselect_b64 s[70:71], -1, 0
	s_cmpk_gt_i32 s18, 0x103f
	s_cbranch_scc1 .LBB0_154
	s_ashr_i32 s19, s18, 31
	s_lshr_b32 s19, s19, 29
	s_add_i32 s19, s18, s19
	s_ashr_i32 s30, s19, 3
	s_and_b32 s19, s19, -8
	s_sub_i32 s18, s18, s19
	s_cmp_lt_i32 s18, 0
	s_movk_i32 s19, 0x209
	s_cselect_b32 s19, s19, 0x208
	s_mul_i32 s18, s19, s18
	s_add_i32 s18, s18, s30
	s_cmpk_lt_u32 s18, 0x1000
	s_cbranch_scc0 .Lg1o_ctx_b
	s_bfe_u32 s19, s18, 0x40005
	s_lshl_b32 s19, s19, 3
	s_and_b32 s30, s18, 7
	s_add_i32 s68, s19, s30
	s_lshr_b32 s19, s18, 9
	s_lshl_b32 s19, s19, 2
	s_bfe_u32 s30, s18, 0x20003
	s_add_i32 s88, s19, s30
	s_branch .Lg1o_done_b
.Lg1o_ctx_b:
	s_sub_i32 s19, s18, 0x1000
	s_and_b32 s30, s19, 1
	s_add_i32 s68, s30, 0x80
	s_lshr_b32 s88, s19, 1
.Lg1o_done_b:
.LBB0_154:
	s_cmp_lt_i32 s88, 16
	s_cselect_b64 s[18:19], -1, 0
	s_cmpk_gt_i32 s68, 0x7f
	s_cselect_b64 s[30:31], -1, 0
	s_ashr_i32 s69, s68, 31
	s_or_b64 s[18:19], s[18:19], s[30:31]
	s_lshl_b64 s[30:31], s[68:69], 15
	v_readlane_b32 s52, v253, 7
	s_and_b64 s[18:19], s[18:19], exec
	v_readlane_b32 s66, v253, 21
	v_readlane_b32 s67, v253, 22
	s_cselect_b32 s19, s3, s66
	s_cselect_b32 s18, s24, s67
	s_add_u32 s72, s19, s30
	s_addc_u32 s73, s18, s31
	s_and_b64 s[18:19], s[70:71], exec
	s_cselect_b32 s18, s73, s83
	s_cselect_b32 s19, s72, s82
	s_ashr_i32 s89, s88, 31
	s_lshl_b64 s[30:31], s[88:89], 15
	s_add_u32 s76, s25, s30
	s_addc_u32 s77, s26, s31
	s_and_b64 s[30:31], s[70:71], exec
	s_cselect_b32 s30, s77, s29
	s_cselect_b32 s31, s76, s28
	s_add_u32 s28, s28, 0x200000
	s_addc_u32 s29, s29, 0
	v_lshl_add_u64 v[54:55], s[82:83], 0, v[148:149]
	s_mov_b32 s52, -2
	s_mov_b64 s[84:85], 0
	v_readlane_b32 s53, v253, 8
	v_readlane_b32 s54, v253, 9
	v_readlane_b32 s55, v253, 10
	v_readlane_b32 s56, v253, 11
	v_readlane_b32 s57, v253, 12
	v_readlane_b32 s58, v253, 13
	v_readlane_b32 s59, v253, 14
	v_readlane_b32 s60, v253, 15
	v_readlane_b32 s61, v253, 16
	v_readlane_b32 s62, v253, 17
	v_readlane_b32 s63, v253, 18
	v_readlane_b32 s64, v253, 19
	v_readlane_b32 s65, v253, 20
	ds_read_b128 v[56:59], v173
	ds_read_b128 v[60:63], v173 offset:1024
	ds_read_b128 v[176:179], v173 offset:2048
	ds_read_b128 v[180:183], v173 offset:3072
	ds_read_b128 v[184:187], v174
	ds_read_b128 v[188:191], v174 offset:1024
	ds_read_b128 v[192:195], v174 offset:2048
	ds_read_b128 v[196:199], v174 offset:3072
	s_add_u32 s53, s82, s84
	s_addc_u32 s56, s83, s85
	s_add_u32 s53, s53, 0x820000
	s_addc_u32 s56, s56, 0
	s_cmp_eq_u32 s84, 0x38e0000
	s_cselect_b32 s57, s18, s56
	s_cselect_b32 s56, s19, s53
	s_cselect_b32 s65, s30, s29
	s_cselect_b32 s64, s31, s28
	v_lshl_add_u64 v[64:65], v[54:55], 0, s[84:85]
	s_mov_b64 s[66:67], 0x414000
	v_lshl_add_u64 v[234:235], v[64:65], 0, s[66:67]
	s_add_i32 m0, s27, 0xc000
	s_mov_b64 s[66:67], 0x416000
	ds_read_b128 v[200:203], v175
	ds_read_b128 v[204:207], v175 offset:1024
	ds_read_b128 v[210:213], v175 offset:2048
	ds_read_b128 v[214:217], v175 offset:3072
	ds_read_b128 v[218:221], v175 offset:4096
	ds_read_b128 v[222:225], v175 offset:5120
	ds_read_b128 v[226:229], v175 offset:6144
	ds_read_b128 v[230:233], v175 offset:7168
	global_load_lds_dwordx4 v[234:235], off
	v_lshl_add_u64 v[64:65], v[64:65], 0, s[66:67]
	s_add_i32 m0, s27, 0xe000
	s_nop 0
	global_load_lds_dwordx4 v[64:65], off
	s_waitcnt vmcnt(8)
	s_waitcnt lgkmcnt(0)
	s_barrier
; #define G8_STA(bufoff, ptr, sg, h) G8_STAGE1(bufoff, (ptr) + (h) * ((sg) ? hA1 : hA0), ((sg) ? voffA1 : voffA0), ((sg) ? r64A1 : r64A0))
; #define G8_STB(bufoff, ptr, sg, h) G8_STAGE1(bufoff, (ptr) + (h) * ((sg) ? hB1 : hB0), ((sg) ? voffB1 : voffB0), ((sg) ? r64B1 : r64B0))
; #define G8_LDA(dst, b, h) do { _Pragma("unroll") for (int m = 0; m < 4; ++m) _Pragma("unroll") for (int k = 0; k < 2; ++k) dst[m][k] = *(const LAS bf16x8*)(lds + G8_SA(b, h) + aoff + m * 2048 + k * 1024); } while (0)
; #define G8_LDB(dst, b, h) do { _Pragma("unroll") for (int n = 0; n < 2; ++n) _Pragma("unroll") for (int k = 0; k < 2; ++k) dst[n][k] = *(const LAS bf16x8*)(lds + G8_SB(b, h) + boff + n * 2048 + k * 1024); } while (0)
; #define G8_MMA(ai, bj, At, Bt) do { __builtin_amdgcn_s_setprio(1); _Pragma("unroll") for (int m = 0; m < 4; ++m) _Pragma("unroll") for (int n = 0; n < 2; ++n) _Pragma("unroll") for (int k = 0; k < 2; ++k) \
;         acc[ai][bj][m][n] = __builtin_amdgcn_mfma_f32_16x16x32_bf16(Bt[n][k], At[m][k], acc[ai][bj][m][n], 0, 0, 0); __builtin_amdgcn_s_setprio(0); } while (0)
; #define G8_WAIT_V(n) asm volatile("s_waitcnt vmcnt(" #n ")" ::: "memory")
; #define G8_WAIT_L(n) asm volatile("s_waitcnt lgkmcnt(" #n ")" ::: "memory")
; #define G8_BAR __builtin_amdgcn_s_barrier()
; #define G8_SCHED __builtin_amdgcn_sched_barrier(0)
; template <class P>
; __device__ __forceinline__ void gemm_phase(LAS unsigned char* lds, const P& p, const int G, const int c) {
;     ...
;             G8_LDB(B0, 0, 0); G8_LDB(B1, 0, 1); G8_SCHED; G8_LDA(At, 0, 0); G8_STA(G8_SA(1, 1), a1, sg1, 1);
;             G8_WAIT_V(8); G8_WAIT_L(0); G8_BAR; G8_MMA(0, 0, At, B0); G8_MMA(0, 1, At, B1); G8_BAR; G8_SCHED;
;             G8_LDA(At, 0, 1); G8_STB(G8_SB(0, 0), b2, sg2, 0); G8_STB(G8_SB(0, 1), b2, sg2, 1); G8_STA(G8_SA(0, 0), a2, sg2, 0);
;             G8_WAIT_V(8); G8_WAIT_L(0); G8_BAR; G8_MMA(1, 0, At, B0); G8_MMA(1, 1, At, B1); G8_BAR; G8_SCHED;
	s_waitcnt lgkmcnt(0)
	v_mfma_f32_16x16x32_bf16 v[98:101], v[56:59], v[200:203], 0
	v_mfma_f32_16x16x32_bf16 v[138:141], v[176:179], v[200:203], 0
	v_mfma_f32_16x16x32_bf16 v[70:73], v[56:59], v[210:213], 0
	v_mfma_f32_16x16x32_bf16 v[114:117], v[176:179], v[210:213], 0
	v_mfma_f32_16x16x32_bf16 v[46:49], v[56:59], v[218:221], 0
	v_mfma_f32_16x16x32_bf16 v[110:113], v[176:179], v[218:221], 0
	v_mfma_f32_16x16x32_bf16 v[38:41], v[56:59], v[226:229], 0
	v_mfma_f32_16x16x32_bf16 v[130:133], v[176:179], v[226:229], 0
	v_mfma_f32_16x16x32_bf16 v[98:101], v[60:63], v[204:207], v[98:101]
	v_mfma_f32_16x16x32_bf16 v[138:141], v[180:183], v[204:207], v[138:141]
	v_mfma_f32_16x16x32_bf16 v[70:73], v[60:63], v[214:217], v[70:73]
	v_mfma_f32_16x16x32_bf16 v[114:117], v[180:183], v[214:217], v[114:117]
	v_mfma_f32_16x16x32_bf16 v[46:49], v[60:63], v[222:225], v[46:49]
	v_mfma_f32_16x16x32_bf16 v[110:113], v[180:183], v[222:225], v[110:113]
	v_mfma_f32_16x16x32_bf16 v[38:41], v[60:63], v[230:233], v[38:41]
	v_mfma_f32_16x16x32_bf16 v[130:133], v[180:183], v[230:233], v[130:133]
	v_mfma_f32_16x16x32_bf16 v[134:137], v[184:187], v[200:203], 0
	v_mfma_f32_16x16x32_bf16 v[74:77], v[192:195], v[200:203], 0
	v_mfma_f32_16x16x32_bf16 v[106:109], v[184:187], v[210:213], 0
	v_mfma_f32_16x16x32_bf16 v[50:53], v[192:195], v[210:213], 0
	v_mfma_f32_16x16x32_bf16 v[102:105], v[184:187], v[218:221], 0
	v_mfma_f32_16x16x32_bf16 v[42:45], v[192:195], v[218:221], 0
	v_mfma_f32_16x16x32_bf16 v[126:129], v[184:187], v[226:229], 0
	v_mfma_f32_16x16x32_bf16 v[34:37], v[192:195], v[226:229], 0
	v_mfma_f32_16x16x32_bf16 v[134:137], v[188:191], v[204:207], v[134:137]
	v_mfma_f32_16x16x32_bf16 v[74:77], v[196:199], v[204:207], v[74:77]
	v_mfma_f32_16x16x32_bf16 v[106:109], v[188:191], v[214:217], v[106:109]
	v_mfma_f32_16x16x32_bf16 v[50:53], v[196:199], v[214:217], v[50:53]
	v_mfma_f32_16x16x32_bf16 v[102:105], v[188:191], v[222:225], v[102:105]
	v_mfma_f32_16x16x32_bf16 v[42:45], v[196:199], v[222:225], v[42:45]
	v_mfma_f32_16x16x32_bf16 v[126:129], v[188:191], v[230:233], v[126:129]
	v_mfma_f32_16x16x32_bf16 v[34:37], v[196:199], v[230:233], v[34:37]
	s_barrier
	s_add_i32 s53, s50, s2
	v_lshl_add_u64 v[234:235], s[64:65], 0, v[142:143]
	s_mov_b32 m0, s53
	ds_read_b128 v[200:203], v175 offset:16384
	ds_read_b128 v[204:207], v175 offset:17408
	ds_read_b128 v[210:213], v175 offset:18432
	ds_read_b128 v[214:217], v175 offset:19456
	ds_read_b128 v[218:221], v175 offset:20480
	ds_read_b128 v[222:225], v175 offset:21504
	ds_read_b128 v[226:229], v175 offset:22528
	ds_read_b128 v[230:233], v175 offset:23552
	global_load_lds_dwordx4 v[234:235], off
	v_lshl_add_u64 v[64:65], v[234:235], 0, s[4:5]
	s_add_i32 m0, s53, 0x2000
	s_add_i32 s53, s51, s2
	global_load_lds_dwordx4 v[64:65], off
	v_lshl_add_u64 v[64:65], v[234:235], 0, s[6:7]
	s_mov_b32 m0, s53
	v_lshl_add_u64 v[236:237], s[56:57], 0, v[144:145]
	global_load_lds_dwordx4 v[64:65], off
	v_lshl_add_u64 v[64:65], v[234:235], 0, s[8:9]
	s_add_i32 m0, s53, 0x2000
	s_nop 0
	global_load_lds_dwordx4 v[64:65], off
	s_mov_b32 m0, s27
	v_lshl_add_u64 v[64:65], v[236:237], 0, s[4:5]
	global_load_lds_dwordx4 v[236:237], off
	s_mov_b32 m0, s33
	s_nop 0
	global_load_lds_dwordx4 v[64:65], off
	s_waitcnt vmcnt(8)
	s_waitcnt lgkmcnt(0)
	s_barrier
	s_waitcnt lgkmcnt(0)
	v_mfma_f32_16x16x32_bf16 v[30:33], v[56:59], v[200:203], 0
	v_mfma_f32_16x16x32_bf16 v[122:125], v[176:179], v[200:203], 0
	v_mfma_f32_16x16x32_bf16 v[22:25], v[56:59], v[210:213], 0
	v_mfma_f32_16x16x32_bf16 v[94:97], v[176:179], v[210:213], 0
	v_mfma_f32_16x16x32_bf16 v[14:17], v[56:59], v[218:221], 0
	v_mfma_f32_16x16x32_bf16 v[90:93], v[176:179], v[218:221], 0
	v_mfma_f32_16x16x32_bf16 v[6:9], v[56:59], v[226:229], 0
	v_mfma_f32_16x16x32_bf16 v[30:33], v[60:63], v[204:207], v[30:33]
	v_mfma_f32_16x16x32_bf16 v[122:125], v[180:183], v[204:207], v[122:125]
	v_mfma_f32_16x16x32_bf16 v[22:25], v[60:63], v[214:217], v[22:25]
	v_mfma_f32_16x16x32_bf16 v[94:97], v[180:183], v[214:217], v[94:97]
	v_mfma_f32_16x16x32_bf16 v[14:17], v[60:63], v[222:225], v[14:17]
	v_mfma_f32_16x16x32_bf16 v[90:93], v[180:183], v[222:225], v[90:93]
	v_mfma_f32_16x16x32_bf16 v[6:9], v[60:63], v[230:233], v[6:9]
	v_mfma_f32_16x16x32_bf16 v[56:59], v[176:179], v[226:229], 0
	v_mfma_f32_16x16x32_bf16 v[56:59], v[180:183], v[230:233], v[56:59]
	v_mfma_f32_16x16x32_bf16 v[78:81], v[184:187], v[210:213], 0
	v_mfma_f32_16x16x32_bf16 v[26:29], v[192:195], v[200:203], 0
	v_mfma_f32_16x16x32_bf16 v[86:89], v[188:191], v[214:217], v[78:81]
	v_mfma_f32_16x16x32_bf16 v[18:21], v[192:195], v[210:213], 0
	v_mfma_f32_16x16x32_bf16 v[78:81], v[184:187], v[218:221], 0
	v_mfma_f32_16x16x32_bf16 v[10:13], v[192:195], v[218:221], 0
	v_mfma_f32_16x16x32_bf16 v[64:67], v[184:187], v[226:229], 0
	v_mfma_f32_16x16x32_bf16 v[2:5], v[192:195], v[226:229], 0
	v_mfma_f32_16x16x32_bf16 v[60:63], v[184:187], v[200:203], 0
	v_mfma_f32_16x16x32_bf16 v[26:29], v[196:199], v[204:207], v[26:29]
	v_mfma_f32_16x16x32_bf16 v[18:21], v[196:199], v[214:217], v[18:21]
	v_mfma_f32_16x16x32_bf16 v[82:85], v[188:191], v[222:225], v[78:81]
	v_mfma_f32_16x16x32_bf16 v[10:13], v[196:199], v[222:225], v[10:13]
	v_mfma_f32_16x16x32_bf16 v[64:67], v[188:191], v[230:233], v[64:67]
	v_mfma_f32_16x16x32_bf16 v[2:5], v[196:199], v[230:233], v[2:5]
	v_mfma_f32_16x16x32_bf16 v[60:63], v[188:191], v[204:207], v[60:63]
	s_branch .Lmid_155
